# G1: phase-2 int8 K-loop top vmcnt(0)->vmcnt(8) (hipcc conservative wait relaxed to the template count)
# speedup vs baseline: 1.0173x; 1.0173x over previous
; #define PG8_STAGE(bufoff, gbase, voff) do { _Pragma("unroll") for (int _i = 0; _i < 2; ++_i) \
;         __builtin_amdgcn_global_load_lds((const unsigned*)((const char*)(gbase) + (voff)[_i]), (PG8_LAS unsigned*)(lds + (bufoff) + ldsw + _i * 8192), 16, 0, 0); } while (0)
; #define PG8_LDA(dst, b, h) do { _Pragma("unroll") for (int m = 0; m < 4; ++m) _Pragma("unroll") for (int k = 0; k < 2; ++k) dst[m][k] = *(const PG8_LAS bf16x8*)(lds + PG8_SA(b, h) + aoff + m * 2048 + k * 1024); } while (0)
; #define PG8_LDB(dst, b, h) do { _Pragma("unroll") for (int n = 0; n < 2; ++n) _Pragma("unroll") for (int k = 0; k < 2; ++k) dst[n][k] = *(const PG8_LAS bf16x8*)(lds + PG8_SB(b, h) + boff + n * 2048 + k * 1024); } while (0)
; #define PG8_WAIT_V(n) asm volatile("s_waitcnt vmcnt(" #n ")" ::: "memory")
; #define PG8_WAIT_L(n) asm volatile("s_waitcnt lgkmcnt(" #n ")" ::: "memory")
; #define PG8_BAR __builtin_amdgcn_s_barrier()
; #define PG8_SCHED __builtin_amdgcn_sched_barrier(0)
; template <class Epi, class Sched, bool ALIGN_EPI = false, bool SP2 = false, bool I8 = false>
; __device__ __forceinline__ void gemm_phase(PG8_LAS unsigned char* lds, const Gemm g, const Sched& S, const Epi& E) {
;     ...
;             const bool last = (t == nt - 2);
;             const char* a1 = cA + (size_t)(t + 1) * kstepA;
;             const char* a2 = last ? nA : cA + (size_t)(t + 2) * kstepA; const char* b2 = last ? nB : cB + (size_t)(t + 2) * kstepB;
;             const char* a3 = a2 + kstepA; const char* b3 = b2 + kstepB;
;             if (last && has_next) S.a_ready(nxt);
;             if constexpr (SP2) {
;             PG8_LDB(B0, 0, 0); PG8_LDB(B1, 0, 1); PG8_SCHED; PG8_LDA(At, 0, 0); PG8_STAGE(PG8_SA(1, 1), a1 + hstepA, voffA);
;             PG8_WAIT_V(8); PG8_WAIT_L(0); PG8_BAR; PG8_MMA(0, 0, At, B0); PG8_MMA(0, 1, At, B1); PG8_BAR; PG8_SCHED;
;             PG8_LDA(At, 0, 1); PG8_STAGE(PG8_SB(0, 0), b2, voffB); PG8_STAGE(PG8_SB(0, 1), b2 + hstepB, voffB); PG8_STAGE(PG8_SA(0, 0), a2, voffA);
.LBB0_278:
	s_waitcnt vmcnt(8)
	ds_read_b128 v[26:29], v202
	ds_read_b128 v[30:33], v202 offset:1024
	ds_read_b128 v[34:37], v202 offset:2048
	ds_read_b128 v[38:41], v202 offset:3072
	ds_read_b128 v[164:167], v203
	ds_read_b128 v[168:171], v203 offset:1024
	ds_read_b128 v[172:175], v203 offset:2048
	ds_read_b128 v[180:183], v203 offset:3072
	s_add_u32 s28, s34, 0x4000
	s_addc_u32 s29, s35, 0
	s_cmp_eq_u32 s76, 28
	s_cselect_b32 s74, s6, s28
	s_cselect_b32 s75, s3, s29
	s_cselect_b32 s72, s13, s19
	s_cselect_b32 s73, s12, s21
	s_add_u32 s70, s74, 0x8000
	s_addc_u32 s71, s75, 0
	v_lshl_add_u64 v[176:177], s[34:35], 0, v[158:159]
	s_add_i32 m0, s25, 0xc000
	ds_read_b128 v[184:187], v204
	ds_read_b128 v[206:209], v204 offset:1024
	ds_read_b128 v[218:221], v204 offset:2048
	ds_read_b128 v[222:225], v204 offset:3072
	ds_read_b128 v[226:229], v204 offset:4096
	ds_read_b128 v[230:233], v204 offset:5120
	ds_read_b128 v[234:237], v204 offset:6144
	ds_read_b128 v[238:241], v204 offset:7168
	global_load_lds_dwordx4 v[176:177], off
	v_lshl_add_u64 v[176:177], s[34:35], 0, v[160:161]
	s_add_i32 m0, s25, 0xe000
	s_nop 0
	global_load_lds_dwordx4 v[176:177], off
	s_waitcnt vmcnt(8)
	s_waitcnt lgkmcnt(0)
	s_barrier
	s_setprio 1
	s_waitcnt lgkmcnt(0)
	v_mfma_i32_16x16x64_i8 v[142:145], v[26:29], v[184:187], v[142:145]
	v_mfma_i32_16x16x64_i8 v[138:141], v[34:37], v[184:187], v[138:141]
	v_mfma_i32_16x16x64_i8 v[134:137], v[26:29], v[218:221], v[134:137]
	v_mfma_i32_16x16x64_i8 v[130:133], v[34:37], v[218:221], v[130:133]
	v_mfma_i32_16x16x64_i8 v[118:121], v[26:29], v[226:229], v[118:121]
	v_mfma_i32_16x16x64_i8 v[114:117], v[34:37], v[226:229], v[114:117]
	v_mfma_i32_16x16x64_i8 v[102:105], v[26:29], v[234:237], v[102:105]
	v_mfma_i32_16x16x64_i8 v[98:101], v[34:37], v[234:237], v[98:101]
	v_mfma_i32_16x16x64_i8 v[142:145], v[30:33], v[206:209], v[142:145]
	v_mfma_i32_16x16x64_i8 v[138:141], v[38:41], v[206:209], v[138:141]
	v_mfma_i32_16x16x64_i8 v[134:137], v[30:33], v[222:225], v[134:137]
	v_mfma_i32_16x16x64_i8 v[130:133], v[38:41], v[222:225], v[130:133]
	v_mfma_i32_16x16x64_i8 v[118:121], v[30:33], v[230:233], v[118:121]
	v_mfma_i32_16x16x64_i8 v[114:117], v[38:41], v[230:233], v[114:117]
	v_mfma_i32_16x16x64_i8 v[102:105], v[30:33], v[238:241], v[102:105]
	v_mfma_i32_16x16x64_i8 v[98:101], v[38:41], v[238:241], v[98:101]
	s_setprio 0
	s_setprio 1
	v_mfma_i32_16x16x64_i8 v[126:129], v[164:167], v[184:187], v[126:129]
	v_mfma_i32_16x16x64_i8 v[122:125], v[172:175], v[184:187], v[122:125]
	v_mfma_i32_16x16x64_i8 v[110:113], v[164:167], v[218:221], v[110:113]
	v_mfma_i32_16x16x64_i8 v[106:109], v[172:175], v[218:221], v[106:109]
	v_mfma_i32_16x16x64_i8 v[94:97], v[164:167], v[226:229], v[94:97]
	v_mfma_i32_16x16x64_i8 v[90:93], v[172:175], v[226:229], v[90:93]
	v_mfma_i32_16x16x64_i8 v[86:89], v[164:167], v[234:237], v[86:89]
	v_mfma_i32_16x16x64_i8 v[82:85], v[172:175], v[234:237], v[82:85]
	v_mfma_i32_16x16x64_i8 v[126:129], v[168:171], v[206:209], v[126:129]
	v_mfma_i32_16x16x64_i8 v[122:125], v[180:183], v[206:209], v[122:125]
	v_mfma_i32_16x16x64_i8 v[110:113], v[168:171], v[222:225], v[110:113]
	v_mfma_i32_16x16x64_i8 v[106:109], v[180:183], v[222:225], v[106:109]
	v_mfma_i32_16x16x64_i8 v[94:97], v[168:171], v[230:233], v[94:97]
	v_mfma_i32_16x16x64_i8 v[90:93], v[180:183], v[230:233], v[90:93]
	v_mfma_i32_16x16x64_i8 v[86:89], v[168:171], v[238:241], v[86:89]
	v_mfma_i32_16x16x64_i8 v[82:85], v[180:183], v[238:241], v[82:85]
	s_setprio 0
	s_barrier
	s_add_i32 s28, s81, s84
	v_lshl_add_u64 v[176:177], s[72:73], 0, v[148:149]
	s_mov_b32 m0, s28
	ds_read_b128 v[184:187], v204 offset:16384
	ds_read_b128 v[206:209], v204 offset:17408
	ds_read_b128 v[218:221], v204 offset:18432
	ds_read_b128 v[222:225], v204 offset:19456
	ds_read_b128 v[226:229], v204 offset:20480
	ds_read_b128 v[230:233], v204 offset:21504
	ds_read_b128 v[234:237], v204 offset:22528
	ds_read_b128 v[238:241], v204 offset:23552
	global_load_lds_dwordx4 v[176:177], off
	s_add_i32 m0, s28, 0x2000
	s_add_u32 s86, s72, 0x4000
	v_lshl_add_u64 v[176:177], s[72:73], 0, v[152:153]
	s_addc_u32 s87, s73, 0
	s_add_i32 s28, s14, s84
	global_load_lds_dwordx4 v[176:177], off
	v_lshl_add_u64 v[176:177], s[86:87], 0, v[148:149]
	s_mov_b32 m0, s28
	s_nop 0
	global_load_lds_dwordx4 v[176:177], off
	v_lshl_add_u64 v[176:177], s[86:87], 0, v[152:153]
	s_add_i32 m0, s28, 0x2000
	s_nop 0
	global_load_lds_dwordx4 v[176:177], off
	v_lshl_add_u64 v[176:177], s[74:75], 0, v[146:147]
	s_mov_b32 m0, s25
	s_nop 0
	global_load_lds_dwordx4 v[176:177], off
	v_lshl_add_u64 v[176:177], s[74:75], 0, v[150:151]
	s_mov_b32 m0, s90
	s_nop 0
	global_load_lds_dwordx4 v[176:177], off
	s_waitcnt vmcnt(8)
	s_waitcnt lgkmcnt(0)
	s_barrier
; #define PG8_STAGE(bufoff, gbase, voff) do { _Pragma("unroll") for (int _i = 0; _i < 2; ++_i) \
;         __builtin_amdgcn_global_load_lds((const unsigned*)((const char*)(gbase) + (voff)[_i]), (PG8_LAS unsigned*)(lds + (bufoff) + ldsw + _i * 8192), 16, 0, 0); } while (0)
; #define PG8_LDA(dst, b, h) do { _Pragma("unroll") for (int m = 0; m < 4; ++m) _Pragma("unroll") for (int k = 0; k < 2; ++k) dst[m][k] = *(const PG8_LAS bf16x8*)(lds + PG8_SA(b, h) + aoff + m * 2048 + k * 1024); } while (0)
; #define PG8_LDB(dst, b, h) do { _Pragma("unroll") for (int n = 0; n < 2; ++n) _Pragma("unroll") for (int k = 0; k < 2; ++k) dst[n][k] = *(const PG8_LAS bf16x8*)(lds + PG8_SB(b, h) + boff + n * 2048 + k * 1024); } while (0)
; #define PG8_WAIT_V(n) asm volatile("s_waitcnt vmcnt(" #n ")" ::: "memory")
; #define PG8_WAIT_L(n) asm volatile("s_waitcnt lgkmcnt(" #n ")" ::: "memory")
; #define PG8_BAR __builtin_amdgcn_s_barrier()
; #define PG8_SCHED __builtin_amdgcn_sched_barrier(0)
; template <class Epi, class Sched, bool ALIGN_EPI = false, bool SP2 = false, bool I8 = false>
; __device__ __forceinline__ void gemm_phase(PG8_LAS unsigned char* lds, const Gemm g, const Sched& S, const Epi& E) {
;     ...
;             PG8_WAIT_V(8); PG8_WAIT_L(0); PG8_BAR; PG8_MMA(1, 0, At, B0); PG8_MMA(1, 1, At, B1); PG8_BAR; PG8_SCHED;
;             PG8_LDB(B0, 1, 0); PG8_LDB(B1, 1, 1); PG8_SCHED; PG8_LDA(At, 1, 0); PG8_STAGE(PG8_SA(0, 1), a2 + hstepA, voffA);
;             PG8_WAIT_V(8); PG8_WAIT_L(0); PG8_BAR; PG8_MMA(0, 0, At, B0); PG8_MMA(0, 1, At, B1); PG8_BAR; PG8_SCHED;
	s_setprio 1
	s_waitcnt lgkmcnt(0)
	v_mfma_i32_16x16x64_i8 v[78:81], v[26:29], v[184:187], v[78:81]
	v_mfma_i32_16x16x64_i8 v[74:77], v[34:37], v[184:187], v[74:77]
	v_mfma_i32_16x16x64_i8 v[70:73], v[26:29], v[218:221], v[70:73]
	v_mfma_i32_16x16x64_i8 v[66:69], v[34:37], v[218:221], v[66:69]
	v_mfma_i32_16x16x64_i8 v[54:57], v[26:29], v[226:229], v[54:57]
	v_mfma_i32_16x16x64_i8 v[50:53], v[34:37], v[226:229], v[50:53]
	v_mfma_i32_16x16x64_i8 v[14:17], v[26:29], v[234:237], v[14:17]
	v_mfma_i32_16x16x64_i8 v[10:13], v[34:37], v[234:237], v[10:13]
	v_mfma_i32_16x16x64_i8 v[78:81], v[30:33], v[206:209], v[78:81]
	v_mfma_i32_16x16x64_i8 v[74:77], v[38:41], v[206:209], v[74:77]
	v_mfma_i32_16x16x64_i8 v[70:73], v[30:33], v[222:225], v[70:73]
	v_mfma_i32_16x16x64_i8 v[66:69], v[38:41], v[222:225], v[66:69]
	v_mfma_i32_16x16x64_i8 v[54:57], v[30:33], v[230:233], v[54:57]
	v_mfma_i32_16x16x64_i8 v[50:53], v[38:41], v[230:233], v[50:53]
	v_mfma_i32_16x16x64_i8 v[14:17], v[30:33], v[238:241], v[14:17]
	v_mfma_i32_16x16x64_i8 v[10:13], v[38:41], v[238:241], v[10:13]
	s_setprio 0
	s_setprio 1
	v_mfma_i32_16x16x64_i8 v[22:25], v[164:167], v[226:229], v[22:25]
	v_mfma_i32_16x16x64_i8 v[18:21], v[172:175], v[226:229], v[18:21]
	v_mfma_i32_16x16x64_i8 v[6:9], v[164:167], v[234:237], v[6:9]
	v_mfma_i32_16x16x64_i8 v[2:5], v[172:175], v[234:237], v[2:5]
	v_mfma_i32_16x16x64_i8 v[26:29], v[164:167], v[184:187], v[62:65]
	v_mfma_i32_16x16x64_i8 v[30:33], v[172:175], v[184:187], v[58:61]
	v_mfma_i32_16x16x64_i8 v[34:37], v[164:167], v[218:221], v[46:49]
	v_mfma_i32_16x16x64_i8 v[38:41], v[172:175], v[218:221], v[42:45]
	v_mfma_i32_16x16x64_i8 v[22:25], v[168:171], v[230:233], v[22:25]
	v_mfma_i32_16x16x64_i8 v[18:21], v[180:183], v[230:233], v[18:21]
	v_mfma_i32_16x16x64_i8 v[6:9], v[168:171], v[238:241], v[6:9]
	v_mfma_i32_16x16x64_i8 v[2:5], v[180:183], v[238:241], v[2:5]
	v_mfma_i32_16x16x64_i8 v[26:29], v[168:171], v[206:209], v[26:29]
	v_mfma_i32_16x16x64_i8 v[30:33], v[180:183], v[206:209], v[30:33]
	v_mfma_i32_16x16x64_i8 v[34:37], v[168:171], v[222:225], v[34:37]
	v_mfma_i32_16x16x64_i8 v[38:41], v[180:183], v[222:225], v[38:41]
	s_setprio 0
	s_barrier
	s_add_i32 s28, 0, 0x18000
	s_add_i32 s29, 0, 0x1c000
	v_add_u32_e32 v62, s28, v200
	v_add_u32_e32 v176, s29, v200
	ds_read_b128 v[42:45], v62
	ds_read_b128 v[46:49], v62 offset:1024
	ds_read_b128 v[58:61], v62 offset:2048
	ds_read_b128 v[62:65], v62 offset:3072
	ds_read_b128 v[164:167], v176
	ds_read_b128 v[168:171], v176 offset:1024
	ds_read_b128 v[172:175], v176 offset:2048
	ds_read_b128 v[180:183], v176 offset:3072
	s_add_u32 s74, s74, 0x4000
	s_addc_u32 s75, s75, 0
	s_mov_b32 m0, s91
	v_lshl_add_u64 v[176:177], s[74:75], 0, v[146:147]
	ds_read_b128 v[184:187], v204 offset:32768
	ds_read_b128 v[206:209], v204 offset:33792
	ds_read_b128 v[218:221], v204 offset:34816
	ds_read_b128 v[222:225], v204 offset:35840
	ds_read_b128 v[226:229], v204 offset:36864
	ds_read_b128 v[230:233], v204 offset:37888
	ds_read_b128 v[234:237], v204 offset:38912
	ds_read_b128 v[238:241], v204 offset:39936
	global_load_lds_dwordx4 v[176:177], off
	v_lshl_add_u64 v[176:177], s[74:75], 0, v[150:151]
	s_mov_b32 m0, s92
	s_nop 0
	global_load_lds_dwordx4 v[176:177], off
	s_waitcnt vmcnt(8)
	s_waitcnt lgkmcnt(0)
	s_barrier
	s_setprio 1
	s_waitcnt lgkmcnt(0)
	v_mfma_i32_16x16x64_i8 v[142:145], v[42:45], v[184:187], v[142:145]
	v_mfma_i32_16x16x64_i8 v[138:141], v[58:61], v[184:187], v[138:141]
	v_mfma_i32_16x16x64_i8 v[134:137], v[42:45], v[218:221], v[134:137]
	v_mfma_i32_16x16x64_i8 v[130:133], v[58:61], v[218:221], v[130:133]
	v_mfma_i32_16x16x64_i8 v[118:121], v[42:45], v[226:229], v[118:121]
	v_mfma_i32_16x16x64_i8 v[114:117], v[58:61], v[226:229], v[114:117]
	v_mfma_i32_16x16x64_i8 v[102:105], v[42:45], v[234:237], v[102:105]
	v_mfma_i32_16x16x64_i8 v[98:101], v[58:61], v[234:237], v[98:101]
	v_mfma_i32_16x16x64_i8 v[142:145], v[46:49], v[206:209], v[142:145]
	v_mfma_i32_16x16x64_i8 v[138:141], v[62:65], v[206:209], v[138:141]
	v_mfma_i32_16x16x64_i8 v[134:137], v[46:49], v[222:225], v[134:137]
	v_mfma_i32_16x16x64_i8 v[130:133], v[62:65], v[222:225], v[130:133]
	v_mfma_i32_16x16x64_i8 v[118:121], v[46:49], v[230:233], v[118:121]
	v_mfma_i32_16x16x64_i8 v[114:117], v[62:65], v[230:233], v[114:117]
	v_mfma_i32_16x16x64_i8 v[102:105], v[46:49], v[238:241], v[102:105]
	v_mfma_i32_16x16x64_i8 v[98:101], v[62:65], v[238:241], v[98:101]
	s_setprio 0
	s_setprio 1
	v_mfma_i32_16x16x64_i8 v[126:129], v[164:167], v[184:187], v[126:129]
	v_mfma_i32_16x16x64_i8 v[122:125], v[172:175], v[184:187], v[122:125]
	v_mfma_i32_16x16x64_i8 v[110:113], v[164:167], v[218:221], v[110:113]
	v_mfma_i32_16x16x64_i8 v[106:109], v[172:175], v[218:221], v[106:109]
	v_mfma_i32_16x16x64_i8 v[94:97], v[164:167], v[226:229], v[94:97]
	v_mfma_i32_16x16x64_i8 v[90:93], v[172:175], v[226:229], v[90:93]
	v_mfma_i32_16x16x64_i8 v[86:89], v[164:167], v[234:237], v[86:89]
	v_mfma_i32_16x16x64_i8 v[82:85], v[172:175], v[234:237], v[82:85]
	v_mfma_i32_16x16x64_i8 v[126:129], v[168:171], v[206:209], v[126:129]
	v_mfma_i32_16x16x64_i8 v[122:125], v[180:183], v[206:209], v[122:125]
	v_mfma_i32_16x16x64_i8 v[110:113], v[168:171], v[222:225], v[110:113]
	v_mfma_i32_16x16x64_i8 v[106:109], v[180:183], v[222:225], v[106:109]
	v_mfma_i32_16x16x64_i8 v[94:97], v[168:171], v[230:233], v[94:97]
	v_mfma_i32_16x16x64_i8 v[90:93], v[180:183], v[230:233], v[90:93]
	v_mfma_i32_16x16x64_i8 v[86:89], v[168:171], v[238:241], v[86:89]
	v_mfma_i32_16x16x64_i8 v[82:85], v[180:183], v[238:241], v[82:85]
	s_setprio 0
	s_barrier
; #define PG8_STAGE(bufoff, gbase, voff) do { _Pragma("unroll") for (int _i = 0; _i < 2; ++_i) \
;         __builtin_amdgcn_global_load_lds((const unsigned*)((const char*)(gbase) + (voff)[_i]), (PG8_LAS unsigned*)(lds + (bufoff) + ldsw + _i * 8192), 16, 0, 0); } while (0)
; #define PG8_LDA(dst, b, h) do { _Pragma("unroll") for (int m = 0; m < 4; ++m) _Pragma("unroll") for (int k = 0; k < 2; ++k) dst[m][k] = *(const PG8_LAS bf16x8*)(lds + PG8_SA(b, h) + aoff + m * 2048 + k * 1024); } while (0)
; #define PG8_WAIT_V(n) asm volatile("s_waitcnt vmcnt(" #n ")" ::: "memory")
; #define PG8_WAIT_L(n) asm volatile("s_waitcnt lgkmcnt(" #n ")" ::: "memory")
; #define PG8_BAR __builtin_amdgcn_s_barrier()
; #define PG8_SCHED __builtin_amdgcn_sched_barrier(0)
; template <class Epi, class Sched, bool ALIGN_EPI = false, bool SP2 = false, bool I8 = false>
; __device__ __forceinline__ void gemm_phase(PG8_LAS unsigned char* lds, const Gemm g, const Sched& S, const Epi& E) {
;     ...
;             PG8_LDA(At, 1, 1); PG8_STAGE(PG8_SB(1, 0), b3, voffB); PG8_STAGE(PG8_SB(1, 1), b3 + hstepB, voffB); PG8_STAGE(PG8_SA(1, 0), a3, voffA);
;             PG8_WAIT_V(8); PG8_WAIT_L(0); PG8_BAR; PG8_MMA(1, 0, At, B0); PG8_MMA(1, 1, At, B1); PG8_BAR; PG8_SCHED;
	s_add_u32 s74, s72, 0x8000
	s_addc_u32 s75, s73, 0
	s_add_i32 s28, s28, s84
	v_lshl_add_u64 v[176:177], s[74:75], 0, v[148:149]
	s_mov_b32 m0, s28
	ds_read_b128 v[184:187], v204 offset:49152
	ds_read_b128 v[206:209], v204 offset:50176
	ds_read_b128 v[218:221], v204 offset:51200
	ds_read_b128 v[222:225], v204 offset:52224
	ds_read_b128 v[226:229], v204 offset:53248
	ds_read_b128 v[230:233], v204 offset:54272
	ds_read_b128 v[234:237], v204 offset:55296
	ds_read_b128 v[238:241], v204 offset:56320
	global_load_lds_dwordx4 v[176:177], off
	s_add_i32 m0, s28, 0x2000
	s_add_u32 s72, s72, 0xc000
	v_lshl_add_u64 v[176:177], s[74:75], 0, v[152:153]
	s_addc_u32 s73, s73, 0
	s_add_i32 s28, s29, s84
	global_load_lds_dwordx4 v[176:177], off
	v_lshl_add_u64 v[176:177], s[72:73], 0, v[148:149]
	s_mov_b32 m0, s28
	s_nop 0
	global_load_lds_dwordx4 v[176:177], off
	v_lshl_add_u64 v[176:177], s[72:73], 0, v[152:153]
	s_add_i32 m0, s28, 0x2000
	s_nop 0
	global_load_lds_dwordx4 v[176:177], off
	v_lshl_add_u64 v[176:177], s[70:71], 0, v[146:147]
	s_mov_b32 m0, s97
	s_nop 0
	global_load_lds_dwordx4 v[176:177], off
	v_lshl_add_u64 v[176:177], s[70:71], 0, v[150:151]
	s_mov_b32 m0, s82
	s_nop 0
	global_load_lds_dwordx4 v[176:177], off
	s_waitcnt vmcnt(8)
	s_waitcnt lgkmcnt(0)
	s_barrier
	s_setprio 1
	s_waitcnt lgkmcnt(0)
	v_mfma_i32_16x16x64_i8 v[78:81], v[42:45], v[184:187], v[78:81]
	v_mfma_i32_16x16x64_i8 v[74:77], v[58:61], v[184:187], v[74:77]
	v_mfma_i32_16x16x64_i8 v[70:73], v[42:45], v[218:221], v[70:73]
	v_mfma_i32_16x16x64_i8 v[66:69], v[58:61], v[218:221], v[66:69]
	v_mfma_i32_16x16x64_i8 v[54:57], v[42:45], v[226:229], v[54:57]
	v_mfma_i32_16x16x64_i8 v[50:53], v[58:61], v[226:229], v[50:53]
	v_mfma_i32_16x16x64_i8 v[14:17], v[42:45], v[234:237], v[14:17]
	v_mfma_i32_16x16x64_i8 v[10:13], v[58:61], v[234:237], v[10:13]
	v_mfma_i32_16x16x64_i8 v[78:81], v[46:49], v[206:209], v[78:81]
	v_mfma_i32_16x16x64_i8 v[74:77], v[62:65], v[206:209], v[74:77]
	v_mfma_i32_16x16x64_i8 v[70:73], v[46:49], v[222:225], v[70:73]
	v_mfma_i32_16x16x64_i8 v[66:69], v[62:65], v[222:225], v[66:69]
	v_mfma_i32_16x16x64_i8 v[54:57], v[46:49], v[230:233], v[54:57]
	v_mfma_i32_16x16x64_i8 v[50:53], v[62:65], v[230:233], v[50:53]
	v_mfma_i32_16x16x64_i8 v[14:17], v[46:49], v[238:241], v[14:17]
	v_mfma_i32_16x16x64_i8 v[10:13], v[62:65], v[238:241], v[10:13]
	s_setprio 0
	s_setprio 1
	v_mfma_i32_16x16x64_i8 v[26:29], v[164:167], v[184:187], v[26:29]
	v_mfma_i32_16x16x64_i8 v[62:65], v[168:171], v[206:209], v[26:29]
	v_mfma_i32_16x16x64_i8 v[26:29], v[172:175], v[184:187], v[30:33]
	v_mfma_i32_16x16x64_i8 v[58:61], v[180:183], v[206:209], v[26:29]
	v_mfma_i32_16x16x64_i8 v[26:29], v[164:167], v[218:221], v[34:37]
	v_mfma_i32_16x16x64_i8 v[46:49], v[168:171], v[222:225], v[26:29]
	v_mfma_i32_16x16x64_i8 v[26:29], v[172:175], v[218:221], v[38:41]
	v_mfma_i32_16x16x64_i8 v[22:25], v[164:167], v[226:229], v[22:25]
	v_mfma_i32_16x16x64_i8 v[18:21], v[172:175], v[226:229], v[18:21]
	v_mfma_i32_16x16x64_i8 v[6:9], v[164:167], v[234:237], v[6:9]
	v_mfma_i32_16x16x64_i8 v[2:5], v[172:175], v[234:237], v[2:5]
	v_mfma_i32_16x16x64_i8 v[42:45], v[180:183], v[222:225], v[26:29]
	v_mfma_i32_16x16x64_i8 v[22:25], v[168:171], v[230:233], v[22:25]
	v_mfma_i32_16x16x64_i8 v[18:21], v[180:183], v[230:233], v[18:21]
	v_mfma_i32_16x16x64_i8 v[6:9], v[168:171], v[238:241], v[6:9]
	v_mfma_i32_16x16x64_i8 v[2:5], v[180:183], v[238:241], v[2:5]
	s_setprio 0
	s_barrier
	s_add_i32 s76, s76, 2
	s_add_u32 s34, s34, 0x10000
	s_addc_u32 s35, s35, 0
	s_add_u32 s19, s19, 0x10000
	s_addc_u32 s21, s21, 0
	s_cmp_gt_u32 s76, 29
	s_cbranch_scc0 .LBB0_278
	s_and_b64 vcc, exec, s[16:17]
	s_cbranch_vccz .LBB0_281
	s_barrier
